# weight-conversion tiles: four source loads issued per wait instead of one load per wait (both inlined copies)
# speedup vs baseline: 1.0927x; 1.0016x over previous
; __device__ void wconv_tile(const Params& P, int l, int tile, unsigned char* smem) {
;     ...
; #pragma unroll 4
;   for (int i = 0; i < 16; ++i) {
;     int kr = g + 4 * i;
;     T[kr * 65 + j] = zero ? 0.f : src[(size_t)(k0 + kr) * ldN + scol];
;   }
.LBB0_467:
	s_or_b64 exec, exec, s[4:5]
	s_addk_i32 s12, 0x1040
	s_add_i32 s13, s13, 16
	s_cmpk_eq_i32 s12, 0x4100
	s_waitcnt vmcnt(0)
	ds_write_b32 v5, v118
	ds_write_b32 v5, v119 offset:1040
	ds_write_b32 v5, v120 offset:2080
	ds_write_b32 v5, v121 offset:3120
	s_cbranch_scc1 .LBB0_476
.LBB0_468:
	v_mov_b32_e32 v118, 0
	v_mov_b32_e32 v119, 0
	v_mov_b32_e32 v120, 0
	v_mov_b32_e32 v121, 0
	v_mov_b32_e32 v6, 0
	v_mov_b32_e32 v7, 0
	s_and_saveexec_b64 s[4:5], s[2:3]
	s_cbranch_execz .LBB0_470
	v_add_u32_e32 v5, s13, v0
	v_ashrrev_i32_e32 v7, 31, v5
	v_mul_lo_u32 v7, s76, v7
	v_mul_lo_u32 v10, s77, v5
	v_mad_u64_u32 v[8:9], s[16:17], s76, v5, 0
	v_add3_u32 v9, v9, v7, v10
	v_lshl_add_u64 v[8:9], v[8:9], 2, v[2:3]
	global_load_dword v118, v[8:9], off
.LBB0_470:
	s_or_b64 exec, exec, s[4:5]
	v_add_u32_e32 v5, s12, v4
	s_and_saveexec_b64 s[4:5], s[2:3]
	s_cbranch_execz .LBB0_472
	v_add3_u32 v6, v0, s13, 4
	v_ashrrev_i32_e32 v7, 31, v6
	v_mul_lo_u32 v8, s76, v7
	v_mul_lo_u32 v9, s77, v6
	v_mad_u64_u32 v[6:7], s[16:17], s76, v6, 0
	v_add3_u32 v7, v7, v8, v9
	v_lshl_add_u64 v[6:7], v[6:7], 2, v[2:3]
	global_load_dword v119, v[6:7], off
.LBB0_472:
	s_or_b64 exec, exec, s[4:5]
	v_mov_b32_e32 v6, 0
	v_mov_b32_e32 v7, 0
	s_and_saveexec_b64 s[4:5], s[2:3]
	s_cbranch_execz .LBB0_474
	v_add3_u32 v7, v0, s13, 8
	v_ashrrev_i32_e32 v8, 31, v7
	v_mul_lo_u32 v10, s76, v8
	v_mul_lo_u32 v11, s77, v7
	v_mad_u64_u32 v[8:9], s[16:17], s76, v7, 0
	v_add3_u32 v9, v9, v10, v11
	v_lshl_add_u64 v[8:9], v[8:9], 2, v[2:3]
	global_load_dword v120, v[8:9], off
.LBB0_474:
	s_or_b64 exec, exec, s[4:5]
	s_and_saveexec_b64 s[4:5], s[2:3]
	s_cbranch_execz .LBB0_467
	v_add3_u32 v6, v0, s13, 12
	v_ashrrev_i32_e32 v7, 31, v6
	v_mul_lo_u32 v8, s76, v7
	v_mul_lo_u32 v9, s77, v6
	v_mad_u64_u32 v[6:7], s[16:17], s76, v6, 0
	v_add3_u32 v7, v7, v8, v9
	v_lshl_add_u64 v[6:7], v[6:7], 2, v[2:3]
	global_load_dword v121, v[6:7], off
	s_branch .LBB0_467

; __device__ void wconv_tile(const Params& P, int l, int tile, unsigned char* smem) {
;     ...
; #pragma unroll 4
;   for (int i = 0; i < 16; ++i) {
;     int kr = g + 4 * i;
;     T[kr * 65 + j] = zero ? 0.f : src[(size_t)(k0 + kr) * ldN + scol];
;   }
.LBB0_647:
	s_or_b64 exec, exec, s[8:9]
	s_addk_i32 s5, 0x1040
	s_add_i32 s12, s12, 16
	s_cmpk_eq_i32 s5, 0x4100
	s_waitcnt vmcnt(0)
	ds_write_b32 v5, v118
	ds_write_b32 v5, v119 offset:1040
	ds_write_b32 v5, v120 offset:2080
	ds_write_b32 v5, v121 offset:3120
	s_cbranch_scc1 .LBB0_656
.LBB0_648:
	v_mov_b32_e32 v118, 0
	v_mov_b32_e32 v119, 0
	v_mov_b32_e32 v120, 0
	v_mov_b32_e32 v121, 0
	v_mov_b32_e32 v6, 0
	v_mov_b32_e32 v7, 0
	s_and_saveexec_b64 s[8:9], s[10:11]
	s_cbranch_execz .LBB0_650
	v_add_u32_e32 v5, s12, v0
	v_ashrrev_i32_e32 v7, 31, v5
	v_mul_lo_u32 v7, s6, v7
	v_mul_lo_u32 v10, s7, v5
	v_mad_u64_u32 v[8:9], s[16:17], s6, v5, 0
	v_add3_u32 v9, v9, v7, v10
	v_lshl_add_u64 v[8:9], v[8:9], 2, v[2:3]
	global_load_dword v118, v[8:9], off
.LBB0_650:
	s_or_b64 exec, exec, s[8:9]
	v_add_u32_e32 v5, s5, v4
	s_and_saveexec_b64 s[8:9], s[10:11]
	s_cbranch_execz .LBB0_652
	v_add3_u32 v6, v0, s12, 4
	v_ashrrev_i32_e32 v7, 31, v6
	v_mul_lo_u32 v8, s6, v7
	v_mul_lo_u32 v9, s7, v6
	v_mad_u64_u32 v[6:7], s[16:17], s6, v6, 0
	v_add3_u32 v7, v7, v8, v9
	v_lshl_add_u64 v[6:7], v[6:7], 2, v[2:3]
	global_load_dword v119, v[6:7], off
.LBB0_652:
	s_or_b64 exec, exec, s[8:9]
	v_mov_b32_e32 v6, 0
	v_mov_b32_e32 v7, 0
	s_and_saveexec_b64 s[8:9], s[10:11]
	s_cbranch_execz .LBB0_654
	v_add3_u32 v7, v0, s12, 8
	v_ashrrev_i32_e32 v8, 31, v7
	v_mul_lo_u32 v10, s6, v8
	v_mul_lo_u32 v11, s7, v7
	v_mad_u64_u32 v[8:9], s[16:17], s6, v7, 0
	v_add3_u32 v9, v9, v10, v11
	v_lshl_add_u64 v[8:9], v[8:9], 2, v[2:3]
	global_load_dword v120, v[8:9], off
.LBB0_654:
	s_or_b64 exec, exec, s[8:9]
	s_and_saveexec_b64 s[8:9], s[10:11]
	s_cbranch_execz .LBB0_647
	v_add3_u32 v6, v0, s12, 12
	v_ashrrev_i32_e32 v7, 31, v6
	v_mul_lo_u32 v8, s6, v7
	v_mul_lo_u32 v9, s7, v6
	v_mad_u64_u32 v[6:7], s[16:17], s6, v6, 0
	v_add3_u32 v7, v7, v8, v9
	v_lshl_add_u64 v[6:7], v[6:7], 2, v[2:3]
	global_load_dword v121, v[6:7], off
	s_branch .LBB0_647
